# v2 + removed s_setprio flips and the redundant post-barrier lgkmcnt(0) in MFMA segments
# speedup vs baseline: 1.0259x; 1.0097x over previous
.LBB0_341:
	s_add_u32 s14, s12, 0xfff00080
	s_addc_u32 s15, s13, -1
	s_add_i32 s30, 0, 0x10000
	s_cmp_eq_u32 s39, 60
	s_cselect_b32 s17, s51, s15
	s_cselect_b32 s16, s50, s14
	v_add_u32_e32 v130, s30, v159
	s_cselect_b32 s15, s53, s1
	s_cselect_b32 s14, s52, s0
	s_add_i32 s42, 0, 0x14000
	s_add_i32 m0, s8, 0xc000
	ds_read_b128 v[152:155], v130
	ds_read_b128 v[162:165], v130 offset:1024
	global_load_lds_dwordx4 v148, s[12:13]
	s_add_i32 m0, s8, 0xe000
	ds_read_b128 v[166:169], v130 offset:2048
	ds_read_b128 v[170:173], v130 offset:3072
	global_load_lds_dwordx4 v150, s[12:13]
	v_add_u32_e32 v130, s42, v159
	ds_read_b128 v[174:177], v130
	ds_read_b128 v[182:185], v130 offset:1024
	ds_read_b128 v[186:189], v130 offset:2048
	ds_read_b128 v[190:193], v130 offset:3072
	ds_read_b128 v[194:197], v161
	ds_read_b128 v[198:201], v161 offset:1024
	ds_read_b128 v[202:205], v161 offset:2048
	ds_read_b128 v[206:209], v161 offset:3072
	ds_read_b128 v[210:213], v161 offset:4096
	ds_read_b128 v[214:217], v161 offset:5120
	ds_read_b128 v[218:221], v161 offset:6144
	ds_read_b128 v[222:225], v161 offset:7168
	s_waitcnt vmcnt(8)
	s_waitcnt lgkmcnt(0)
	s_barrier
	v_mfma_f32_16x16x32_bf16 v[126:129], v[152:155], v[194:197], v[126:129]
	v_mfma_f32_16x16x32_bf16 v[126:129], v[162:165], v[198:201], v[126:129]
	v_mfma_f32_16x16x32_bf16 v[122:125], v[166:169], v[194:197], v[122:125]
	v_mfma_f32_16x16x32_bf16 v[122:125], v[170:173], v[198:201], v[122:125]
	v_mfma_f32_16x16x32_bf16 v[110:113], v[152:155], v[202:205], v[110:113]
	v_mfma_f32_16x16x32_bf16 v[110:113], v[162:165], v[206:209], v[110:113]
	v_mfma_f32_16x16x32_bf16 v[106:109], v[166:169], v[202:205], v[106:109]
	v_mfma_f32_16x16x32_bf16 v[106:109], v[170:173], v[206:209], v[106:109]
	v_mfma_f32_16x16x32_bf16 v[94:97], v[152:155], v[210:213], v[94:97]
	v_mfma_f32_16x16x32_bf16 v[94:97], v[162:165], v[214:217], v[94:97]
	v_mfma_f32_16x16x32_bf16 v[90:93], v[166:169], v[210:213], v[90:93]
	v_mfma_f32_16x16x32_bf16 v[90:93], v[170:173], v[214:217], v[90:93]
	v_mfma_f32_16x16x32_bf16 v[78:81], v[152:155], v[218:221], v[78:81]
	v_mfma_f32_16x16x32_bf16 v[78:81], v[162:165], v[222:225], v[78:81]
	v_mfma_f32_16x16x32_bf16 v[74:77], v[166:169], v[218:221], v[74:77]
	v_mfma_f32_16x16x32_bf16 v[74:77], v[170:173], v[222:225], v[74:77]
	v_mfma_f32_16x16x32_bf16 v[118:121], v[174:177], v[194:197], v[118:121]
	v_mfma_f32_16x16x32_bf16 v[118:121], v[182:185], v[198:201], v[118:121]
	v_mfma_f32_16x16x32_bf16 v[114:117], v[186:189], v[194:197], v[114:117]
	v_mfma_f32_16x16x32_bf16 v[114:117], v[190:193], v[198:201], v[114:117]
	v_mfma_f32_16x16x32_bf16 v[102:105], v[174:177], v[202:205], v[102:105]
	v_mfma_f32_16x16x32_bf16 v[102:105], v[182:185], v[206:209], v[102:105]
	v_mfma_f32_16x16x32_bf16 v[98:101], v[186:189], v[202:205], v[98:101]
	v_mfma_f32_16x16x32_bf16 v[98:101], v[190:193], v[206:209], v[98:101]
	v_mfma_f32_16x16x32_bf16 v[86:89], v[174:177], v[210:213], v[86:89]
	v_mfma_f32_16x16x32_bf16 v[86:89], v[182:185], v[214:217], v[86:89]
	v_mfma_f32_16x16x32_bf16 v[82:85], v[186:189], v[210:213], v[82:85]
	v_mfma_f32_16x16x32_bf16 v[82:85], v[190:193], v[214:217], v[82:85]
	v_mfma_f32_16x16x32_bf16 v[70:73], v[174:177], v[218:221], v[70:73]
	v_mfma_f32_16x16x32_bf16 v[70:73], v[182:185], v[222:225], v[70:73]
	v_mfma_f32_16x16x32_bf16 v[66:69], v[186:189], v[218:221], v[66:69]
	v_mfma_f32_16x16x32_bf16 v[66:69], v[190:193], v[222:225], v[66:69]
	s_barrier
	s_add_i32 m0, s28, 0x10000
	ds_read_b128 v[194:197], v161 offset:16384
	ds_read_b128 v[198:201], v161 offset:17408
	global_load_lds_dwordx4 v144, s[14:15]
	s_add_i32 m0, s28, 0x12000
	s_add_u32 s98, s14, 0x100000
	s_addc_u32 s99, s15, 0
	ds_read_b128 v[202:205], v161 offset:18432
	global_load_lds_dwordx4 v140, s[14:15]
	s_add_i32 m0, s28, 0x14000
	ds_read_b128 v[206:209], v161 offset:19456
	ds_read_b128 v[210:213], v161 offset:20480
	global_load_lds_dwordx4 v144, s[98:99]
	s_add_i32 m0, s28, 0x16000
	ds_read_b128 v[214:217], v161 offset:21504
	ds_read_b128 v[218:221], v161 offset:22528
	global_load_lds_dwordx4 v140, s[98:99]
	s_mov_b32 m0, s8
	ds_read_b128 v[222:225], v161 offset:23552
	global_load_lds_dwordx4 v146, s[16:17]
	s_mov_b32 m0, s9
	s_nop 0
	global_load_lds_dwordx4 v142, s[16:17]
	s_waitcnt vmcnt(8)
	s_waitcnt lgkmcnt(0)
	s_barrier
	v_mfma_f32_16x16x32_bf16 v[62:65], v[152:155], v[194:197], v[62:65]
	v_mfma_f32_16x16x32_bf16 v[62:65], v[162:165], v[198:201], v[62:65]
	v_mfma_f32_16x16x32_bf16 v[58:61], v[166:169], v[194:197], v[58:61]
	v_mfma_f32_16x16x32_bf16 v[58:61], v[170:173], v[198:201], v[58:61]
	v_mfma_f32_16x16x32_bf16 v[46:49], v[152:155], v[202:205], v[46:49]
	v_mfma_f32_16x16x32_bf16 v[46:49], v[162:165], v[206:209], v[46:49]
	v_mfma_f32_16x16x32_bf16 v[42:45], v[166:169], v[202:205], v[42:45]
	v_mfma_f32_16x16x32_bf16 v[42:45], v[170:173], v[206:209], v[42:45]
	v_mfma_f32_16x16x32_bf16 v[30:33], v[152:155], v[210:213], v[30:33]
	v_mfma_f32_16x16x32_bf16 v[30:33], v[162:165], v[214:217], v[30:33]
	v_mfma_f32_16x16x32_bf16 v[26:29], v[166:169], v[210:213], v[26:29]
	v_mfma_f32_16x16x32_bf16 v[26:29], v[170:173], v[214:217], v[26:29]
	v_mfma_f32_16x16x32_bf16 v[14:17], v[152:155], v[218:221], v[14:17]
	v_mfma_f32_16x16x32_bf16 v[14:17], v[162:165], v[222:225], v[14:17]
	v_mfma_f32_16x16x32_bf16 v[10:13], v[166:169], v[218:221], v[10:13]
	v_mfma_f32_16x16x32_bf16 v[10:13], v[170:173], v[222:225], v[10:13]
	v_mfma_f32_16x16x32_bf16 v[54:57], v[174:177], v[194:197], v[54:57]
	v_mfma_f32_16x16x32_bf16 v[54:57], v[182:185], v[198:201], v[54:57]
	v_mfma_f32_16x16x32_bf16 v[50:53], v[186:189], v[194:197], v[50:53]
	v_mfma_f32_16x16x32_bf16 v[50:53], v[190:193], v[198:201], v[50:53]
	v_mfma_f32_16x16x32_bf16 v[38:41], v[174:177], v[202:205], v[38:41]
	v_mfma_f32_16x16x32_bf16 v[38:41], v[182:185], v[206:209], v[38:41]
	v_mfma_f32_16x16x32_bf16 v[34:37], v[186:189], v[202:205], v[34:37]
	v_mfma_f32_16x16x32_bf16 v[34:37], v[190:193], v[206:209], v[34:37]
	v_mfma_f32_16x16x32_bf16 v[22:25], v[174:177], v[210:213], v[22:25]
	v_mfma_f32_16x16x32_bf16 v[22:25], v[182:185], v[214:217], v[22:25]
	v_mfma_f32_16x16x32_bf16 v[18:21], v[186:189], v[210:213], v[18:21]
	v_mfma_f32_16x16x32_bf16 v[18:21], v[190:193], v[214:217], v[18:21]
	v_mfma_f32_16x16x32_bf16 v[6:9], v[174:177], v[218:221], v[6:9]
	v_mfma_f32_16x16x32_bf16 v[6:9], v[182:185], v[222:225], v[6:9]
	v_mfma_f32_16x16x32_bf16 v[2:5], v[186:189], v[218:221], v[2:5]
	v_mfma_f32_16x16x32_bf16 v[2:5], v[190:193], v[222:225], v[2:5]
	s_barrier
	s_add_u32 s100, s16, 0x100000
	s_addc_u32 s101, s17, 0
	s_mov_b32 m0, s29
	s_add_i32 s30, 0, 0x18000
	v_add_u32_e32 v130, s30, v159
	s_add_i32 s31, 0, 0x1c000
	ds_read_b128 v[152:155], v130
	ds_read_b128 v[162:165], v130 offset:1024
	global_load_lds_dwordx4 v146, s[100:101]
	s_mov_b32 m0, s36
	ds_read_b128 v[166:169], v130 offset:2048
	ds_read_b128 v[170:173], v130 offset:3072
	global_load_lds_dwordx4 v142, s[100:101]
	v_add_u32_e32 v130, s31, v159
	ds_read_b128 v[174:177], v130
	ds_read_b128 v[182:185], v130 offset:1024
	ds_read_b128 v[186:189], v130 offset:2048
	ds_read_b128 v[190:193], v130 offset:3072
	ds_read_b128 v[194:197], v161 offset:32768
	ds_read_b128 v[198:201], v161 offset:33792
	ds_read_b128 v[202:205], v161 offset:34816
	ds_read_b128 v[206:209], v161 offset:35840
	ds_read_b128 v[210:213], v161 offset:36864
	ds_read_b128 v[214:217], v161 offset:37888
	ds_read_b128 v[218:221], v161 offset:38912
	ds_read_b128 v[222:225], v161 offset:39936
	s_waitcnt vmcnt(8)
	s_waitcnt lgkmcnt(0)
	s_barrier
	v_mfma_f32_16x16x32_bf16 v[126:129], v[152:155], v[194:197], v[126:129]
	v_mfma_f32_16x16x32_bf16 v[126:129], v[162:165], v[198:201], v[126:129]
	v_mfma_f32_16x16x32_bf16 v[122:125], v[166:169], v[194:197], v[122:125]
	v_mfma_f32_16x16x32_bf16 v[122:125], v[170:173], v[198:201], v[122:125]
	v_mfma_f32_16x16x32_bf16 v[110:113], v[152:155], v[202:205], v[110:113]
	v_mfma_f32_16x16x32_bf16 v[110:113], v[162:165], v[206:209], v[110:113]
	v_mfma_f32_16x16x32_bf16 v[106:109], v[166:169], v[202:205], v[106:109]
	v_mfma_f32_16x16x32_bf16 v[106:109], v[170:173], v[206:209], v[106:109]
	v_mfma_f32_16x16x32_bf16 v[94:97], v[152:155], v[210:213], v[94:97]
	v_mfma_f32_16x16x32_bf16 v[94:97], v[162:165], v[214:217], v[94:97]
	v_mfma_f32_16x16x32_bf16 v[90:93], v[166:169], v[210:213], v[90:93]
	v_mfma_f32_16x16x32_bf16 v[90:93], v[170:173], v[214:217], v[90:93]
	v_mfma_f32_16x16x32_bf16 v[78:81], v[152:155], v[218:221], v[78:81]
	v_mfma_f32_16x16x32_bf16 v[78:81], v[162:165], v[222:225], v[78:81]
	v_mfma_f32_16x16x32_bf16 v[74:77], v[166:169], v[218:221], v[74:77]
	v_mfma_f32_16x16x32_bf16 v[74:77], v[170:173], v[222:225], v[74:77]
	v_mfma_f32_16x16x32_bf16 v[118:121], v[174:177], v[194:197], v[118:121]
	v_mfma_f32_16x16x32_bf16 v[118:121], v[182:185], v[198:201], v[118:121]
	v_mfma_f32_16x16x32_bf16 v[114:117], v[186:189], v[194:197], v[114:117]
	v_mfma_f32_16x16x32_bf16 v[114:117], v[190:193], v[198:201], v[114:117]
	v_mfma_f32_16x16x32_bf16 v[102:105], v[174:177], v[202:205], v[102:105]
	v_mfma_f32_16x16x32_bf16 v[102:105], v[182:185], v[206:209], v[102:105]
	v_mfma_f32_16x16x32_bf16 v[98:101], v[186:189], v[202:205], v[98:101]
	v_mfma_f32_16x16x32_bf16 v[98:101], v[190:193], v[206:209], v[98:101]
	v_mfma_f32_16x16x32_bf16 v[86:89], v[174:177], v[210:213], v[86:89]
	v_mfma_f32_16x16x32_bf16 v[86:89], v[182:185], v[214:217], v[86:89]
	v_mfma_f32_16x16x32_bf16 v[82:85], v[186:189], v[210:213], v[82:85]
	v_mfma_f32_16x16x32_bf16 v[82:85], v[190:193], v[214:217], v[82:85]
	v_mfma_f32_16x16x32_bf16 v[70:73], v[174:177], v[218:221], v[70:73]
	v_mfma_f32_16x16x32_bf16 v[70:73], v[182:185], v[222:225], v[70:73]
	v_mfma_f32_16x16x32_bf16 v[66:69], v[186:189], v[218:221], v[66:69]
	v_mfma_f32_16x16x32_bf16 v[66:69], v[190:193], v[222:225], v[66:69]
	s_barrier
	s_add_u32 s14, s14, 0x80
	s_addc_u32 s15, s15, 0
	s_add_i32 m0, s28, 0x18000
	ds_read_b128 v[194:197], v161 offset:49152
	ds_read_b128 v[198:201], v161 offset:50176
	global_load_lds_dwordx4 v144, s[14:15]
	s_add_i32 m0, s28, 0x1a000
	s_add_u32 s98, s98, 0x80
	s_addc_u32 s99, s99, 0
	ds_read_b128 v[202:205], v161 offset:51200
	global_load_lds_dwordx4 v140, s[14:15]
	s_add_i32 m0, s28, 0x1c000
	ds_read_b128 v[206:209], v161 offset:52224
	ds_read_b128 v[210:213], v161 offset:53248
	global_load_lds_dwordx4 v144, s[98:99]
	s_add_i32 m0, s28, 0x1e000
	s_add_u32 s16, s16, 0x80
	s_addc_u32 s17, s17, 0
	ds_read_b128 v[214:217], v161 offset:54272
	ds_read_b128 v[218:221], v161 offset:55296
	global_load_lds_dwordx4 v140, s[98:99]
	s_mov_b32 m0, s45
	ds_read_b128 v[222:225], v161 offset:56320
	global_load_lds_dwordx4 v146, s[16:17]
	s_mov_b32 m0, s46
	s_nop 0
	global_load_lds_dwordx4 v142, s[16:17]
	s_waitcnt vmcnt(8)
	s_waitcnt lgkmcnt(0)
	s_barrier
	v_mfma_f32_16x16x32_bf16 v[62:65], v[152:155], v[194:197], v[62:65]
	v_mfma_f32_16x16x32_bf16 v[62:65], v[162:165], v[198:201], v[62:65]
	v_mfma_f32_16x16x32_bf16 v[58:61], v[166:169], v[194:197], v[58:61]
	v_mfma_f32_16x16x32_bf16 v[58:61], v[170:173], v[198:201], v[58:61]
	v_mfma_f32_16x16x32_bf16 v[46:49], v[152:155], v[202:205], v[46:49]
	v_mfma_f32_16x16x32_bf16 v[46:49], v[162:165], v[206:209], v[46:49]
	v_mfma_f32_16x16x32_bf16 v[42:45], v[166:169], v[202:205], v[42:45]
	v_mfma_f32_16x16x32_bf16 v[42:45], v[170:173], v[206:209], v[42:45]
	v_mfma_f32_16x16x32_bf16 v[30:33], v[152:155], v[210:213], v[30:33]
	v_mfma_f32_16x16x32_bf16 v[30:33], v[162:165], v[214:217], v[30:33]
	v_mfma_f32_16x16x32_bf16 v[26:29], v[166:169], v[210:213], v[26:29]
	v_mfma_f32_16x16x32_bf16 v[26:29], v[170:173], v[214:217], v[26:29]
	v_mfma_f32_16x16x32_bf16 v[14:17], v[152:155], v[218:221], v[14:17]
	v_mfma_f32_16x16x32_bf16 v[14:17], v[162:165], v[222:225], v[14:17]
	v_mfma_f32_16x16x32_bf16 v[10:13], v[166:169], v[218:221], v[10:13]
	v_mfma_f32_16x16x32_bf16 v[10:13], v[170:173], v[222:225], v[10:13]
	v_mfma_f32_16x16x32_bf16 v[54:57], v[174:177], v[194:197], v[54:57]
	v_mfma_f32_16x16x32_bf16 v[54:57], v[182:185], v[198:201], v[54:57]
	v_mfma_f32_16x16x32_bf16 v[50:53], v[186:189], v[194:197], v[50:53]
	v_mfma_f32_16x16x32_bf16 v[50:53], v[190:193], v[198:201], v[50:53]
	v_mfma_f32_16x16x32_bf16 v[38:41], v[174:177], v[202:205], v[38:41]
	v_mfma_f32_16x16x32_bf16 v[38:41], v[182:185], v[206:209], v[38:41]
	v_mfma_f32_16x16x32_bf16 v[34:37], v[186:189], v[202:205], v[34:37]
	v_mfma_f32_16x16x32_bf16 v[34:37], v[190:193], v[206:209], v[34:37]
	v_mfma_f32_16x16x32_bf16 v[22:25], v[174:177], v[210:213], v[22:25]
	v_mfma_f32_16x16x32_bf16 v[22:25], v[182:185], v[214:217], v[22:25]
	v_mfma_f32_16x16x32_bf16 v[18:21], v[186:189], v[210:213], v[18:21]
	v_mfma_f32_16x16x32_bf16 v[18:21], v[190:193], v[214:217], v[18:21]
	v_mfma_f32_16x16x32_bf16 v[6:9], v[174:177], v[218:221], v[6:9]
	v_mfma_f32_16x16x32_bf16 v[6:9], v[182:185], v[222:225], v[6:9]
	v_mfma_f32_16x16x32_bf16 v[2:5], v[186:189], v[218:221], v[2:5]
	v_mfma_f32_16x16x32_bf16 v[2:5], v[190:193], v[222:225], v[2:5]
	s_barrier
	s_add_i32 s39, s39, 2
	s_add_u32 s12, s12, 0x100
	s_addc_u32 s13, s13, 0
	s_add_u32 s0, s0, 0x100
	s_addc_u32 s1, s1, 0
	s_cmp_gt_u32 s39, 61
	s_cbranch_scc0 .LBB0_341
	s_and_b64 vcc, exec, s[34:35]
	s_cbranch_vccz .LBB0_344
	s_barrier

.LBB0_572:
	s_add_u32 s14, s12, 0xfff00080
	s_addc_u32 s15, s13, -1
	s_add_i32 s30, 0, 0x10000
	s_cmp_eq_u32 s35, 60
	s_cselect_b32 s17, s51, s15
	s_cselect_b32 s16, s50, s14
	v_add_u32_e32 v130, s30, v159
	s_cselect_b32 s15, s53, s1
	s_cselect_b32 s14, s52, s0
	s_add_i32 s42, 0, 0x14000
	s_add_i32 m0, s8, 0xc000
	ds_read_b128 v[152:155], v130
	ds_read_b128 v[162:165], v130 offset:1024
	global_load_lds_dwordx4 v148, s[12:13]
	s_add_i32 m0, s8, 0xe000
	ds_read_b128 v[166:169], v130 offset:2048
	ds_read_b128 v[170:173], v130 offset:3072
	global_load_lds_dwordx4 v150, s[12:13]
	v_add_u32_e32 v130, s42, v159
	ds_read_b128 v[174:177], v130
	ds_read_b128 v[182:185], v130 offset:1024
	ds_read_b128 v[186:189], v130 offset:2048
	ds_read_b128 v[190:193], v130 offset:3072
	ds_read_b128 v[194:197], v161
	ds_read_b128 v[198:201], v161 offset:1024
	ds_read_b128 v[202:205], v161 offset:2048
	ds_read_b128 v[206:209], v161 offset:3072
	ds_read_b128 v[210:213], v161 offset:4096
	ds_read_b128 v[214:217], v161 offset:5120
	ds_read_b128 v[218:221], v161 offset:6144
	ds_read_b128 v[222:225], v161 offset:7168
	s_waitcnt vmcnt(8)
	s_waitcnt lgkmcnt(0)
	s_barrier
	v_mfma_f32_16x16x32_bf16 v[126:129], v[152:155], v[194:197], v[126:129]
	v_mfma_f32_16x16x32_bf16 v[126:129], v[162:165], v[198:201], v[126:129]
	v_mfma_f32_16x16x32_bf16 v[122:125], v[166:169], v[194:197], v[122:125]
	v_mfma_f32_16x16x32_bf16 v[122:125], v[170:173], v[198:201], v[122:125]
	v_mfma_f32_16x16x32_bf16 v[110:113], v[152:155], v[202:205], v[110:113]
	v_mfma_f32_16x16x32_bf16 v[110:113], v[162:165], v[206:209], v[110:113]
	v_mfma_f32_16x16x32_bf16 v[106:109], v[166:169], v[202:205], v[106:109]
	v_mfma_f32_16x16x32_bf16 v[106:109], v[170:173], v[206:209], v[106:109]
	v_mfma_f32_16x16x32_bf16 v[94:97], v[152:155], v[210:213], v[94:97]
	v_mfma_f32_16x16x32_bf16 v[94:97], v[162:165], v[214:217], v[94:97]
	v_mfma_f32_16x16x32_bf16 v[90:93], v[166:169], v[210:213], v[90:93]
	v_mfma_f32_16x16x32_bf16 v[90:93], v[170:173], v[214:217], v[90:93]
	v_mfma_f32_16x16x32_bf16 v[78:81], v[152:155], v[218:221], v[78:81]
	v_mfma_f32_16x16x32_bf16 v[78:81], v[162:165], v[222:225], v[78:81]
	v_mfma_f32_16x16x32_bf16 v[74:77], v[166:169], v[218:221], v[74:77]
	v_mfma_f32_16x16x32_bf16 v[74:77], v[170:173], v[222:225], v[74:77]
	v_mfma_f32_16x16x32_bf16 v[118:121], v[174:177], v[194:197], v[118:121]
	v_mfma_f32_16x16x32_bf16 v[118:121], v[182:185], v[198:201], v[118:121]
	v_mfma_f32_16x16x32_bf16 v[114:117], v[186:189], v[194:197], v[114:117]
	v_mfma_f32_16x16x32_bf16 v[114:117], v[190:193], v[198:201], v[114:117]
	v_mfma_f32_16x16x32_bf16 v[102:105], v[174:177], v[202:205], v[102:105]
	v_mfma_f32_16x16x32_bf16 v[102:105], v[182:185], v[206:209], v[102:105]
	v_mfma_f32_16x16x32_bf16 v[98:101], v[186:189], v[202:205], v[98:101]
	v_mfma_f32_16x16x32_bf16 v[98:101], v[190:193], v[206:209], v[98:101]
	v_mfma_f32_16x16x32_bf16 v[86:89], v[174:177], v[210:213], v[86:89]
	v_mfma_f32_16x16x32_bf16 v[86:89], v[182:185], v[214:217], v[86:89]
	v_mfma_f32_16x16x32_bf16 v[82:85], v[186:189], v[210:213], v[82:85]
	v_mfma_f32_16x16x32_bf16 v[82:85], v[190:193], v[214:217], v[82:85]
	v_mfma_f32_16x16x32_bf16 v[70:73], v[174:177], v[218:221], v[70:73]
	v_mfma_f32_16x16x32_bf16 v[70:73], v[182:185], v[222:225], v[70:73]
	v_mfma_f32_16x16x32_bf16 v[66:69], v[186:189], v[218:221], v[66:69]
	v_mfma_f32_16x16x32_bf16 v[66:69], v[190:193], v[222:225], v[66:69]
	s_barrier
	s_add_i32 m0, s28, 0x10000
	ds_read_b128 v[194:197], v161 offset:16384
	ds_read_b128 v[198:201], v161 offset:17408
	global_load_lds_dwordx4 v144, s[14:15]
	s_add_i32 m0, s28, 0x12000
	s_add_u32 s98, s14, 0x100000
	s_addc_u32 s99, s15, 0
	ds_read_b128 v[202:205], v161 offset:18432
	global_load_lds_dwordx4 v140, s[14:15]
	s_add_i32 m0, s28, 0x14000
	ds_read_b128 v[206:209], v161 offset:19456
	ds_read_b128 v[210:213], v161 offset:20480
	global_load_lds_dwordx4 v144, s[98:99]
	s_add_i32 m0, s28, 0x16000
	ds_read_b128 v[214:217], v161 offset:21504
	ds_read_b128 v[218:221], v161 offset:22528
	global_load_lds_dwordx4 v140, s[98:99]
	s_mov_b32 m0, s8
	ds_read_b128 v[222:225], v161 offset:23552
	global_load_lds_dwordx4 v146, s[16:17]
	s_mov_b32 m0, s9
	s_nop 0
	global_load_lds_dwordx4 v142, s[16:17]
	s_waitcnt vmcnt(8)
	s_waitcnt lgkmcnt(0)
	s_barrier
	v_mfma_f32_16x16x32_bf16 v[62:65], v[152:155], v[194:197], v[62:65]
	v_mfma_f32_16x16x32_bf16 v[62:65], v[162:165], v[198:201], v[62:65]
	v_mfma_f32_16x16x32_bf16 v[58:61], v[166:169], v[194:197], v[58:61]
	v_mfma_f32_16x16x32_bf16 v[58:61], v[170:173], v[198:201], v[58:61]
	v_mfma_f32_16x16x32_bf16 v[46:49], v[152:155], v[202:205], v[46:49]
	v_mfma_f32_16x16x32_bf16 v[46:49], v[162:165], v[206:209], v[46:49]
	v_mfma_f32_16x16x32_bf16 v[42:45], v[166:169], v[202:205], v[42:45]
	v_mfma_f32_16x16x32_bf16 v[42:45], v[170:173], v[206:209], v[42:45]
	v_mfma_f32_16x16x32_bf16 v[30:33], v[152:155], v[210:213], v[30:33]
	v_mfma_f32_16x16x32_bf16 v[30:33], v[162:165], v[214:217], v[30:33]
	v_mfma_f32_16x16x32_bf16 v[26:29], v[166:169], v[210:213], v[26:29]
	v_mfma_f32_16x16x32_bf16 v[26:29], v[170:173], v[214:217], v[26:29]
	v_mfma_f32_16x16x32_bf16 v[14:17], v[152:155], v[218:221], v[14:17]
	v_mfma_f32_16x16x32_bf16 v[14:17], v[162:165], v[222:225], v[14:17]
	v_mfma_f32_16x16x32_bf16 v[10:13], v[166:169], v[218:221], v[10:13]
	v_mfma_f32_16x16x32_bf16 v[10:13], v[170:173], v[222:225], v[10:13]
	v_mfma_f32_16x16x32_bf16 v[54:57], v[174:177], v[194:197], v[54:57]
	v_mfma_f32_16x16x32_bf16 v[54:57], v[182:185], v[198:201], v[54:57]
	v_mfma_f32_16x16x32_bf16 v[50:53], v[186:189], v[194:197], v[50:53]
	v_mfma_f32_16x16x32_bf16 v[50:53], v[190:193], v[198:201], v[50:53]
	v_mfma_f32_16x16x32_bf16 v[38:41], v[174:177], v[202:205], v[38:41]
	v_mfma_f32_16x16x32_bf16 v[38:41], v[182:185], v[206:209], v[38:41]
	v_mfma_f32_16x16x32_bf16 v[34:37], v[186:189], v[202:205], v[34:37]
	v_mfma_f32_16x16x32_bf16 v[34:37], v[190:193], v[206:209], v[34:37]
	v_mfma_f32_16x16x32_bf16 v[22:25], v[174:177], v[210:213], v[22:25]
	v_mfma_f32_16x16x32_bf16 v[22:25], v[182:185], v[214:217], v[22:25]
	v_mfma_f32_16x16x32_bf16 v[18:21], v[186:189], v[210:213], v[18:21]
	v_mfma_f32_16x16x32_bf16 v[18:21], v[190:193], v[214:217], v[18:21]
	v_mfma_f32_16x16x32_bf16 v[6:9], v[174:177], v[218:221], v[6:9]
	v_mfma_f32_16x16x32_bf16 v[6:9], v[182:185], v[222:225], v[6:9]
	v_mfma_f32_16x16x32_bf16 v[2:5], v[186:189], v[218:221], v[2:5]
	v_mfma_f32_16x16x32_bf16 v[2:5], v[190:193], v[222:225], v[2:5]
	s_barrier
	s_add_u32 s100, s16, 0x100000
	s_addc_u32 s101, s17, 0
	s_mov_b32 m0, s29
	s_add_i32 s30, 0, 0x18000
	v_add_u32_e32 v130, s30, v159
	s_add_i32 s31, 0, 0x1c000
	ds_read_b128 v[152:155], v130
	ds_read_b128 v[162:165], v130 offset:1024
	global_load_lds_dwordx4 v146, s[100:101]
	s_mov_b32 m0, s36
	ds_read_b128 v[166:169], v130 offset:2048
	ds_read_b128 v[170:173], v130 offset:3072
	global_load_lds_dwordx4 v142, s[100:101]
	v_add_u32_e32 v130, s31, v159
	ds_read_b128 v[174:177], v130
	ds_read_b128 v[182:185], v130 offset:1024
	ds_read_b128 v[186:189], v130 offset:2048
	ds_read_b128 v[190:193], v130 offset:3072
	ds_read_b128 v[194:197], v161 offset:32768
	ds_read_b128 v[198:201], v161 offset:33792
	ds_read_b128 v[202:205], v161 offset:34816
	ds_read_b128 v[206:209], v161 offset:35840
	ds_read_b128 v[210:213], v161 offset:36864
	ds_read_b128 v[214:217], v161 offset:37888
	ds_read_b128 v[218:221], v161 offset:38912
	ds_read_b128 v[222:225], v161 offset:39936
	s_waitcnt vmcnt(8)
	s_waitcnt lgkmcnt(0)
	s_barrier
	v_mfma_f32_16x16x32_bf16 v[126:129], v[152:155], v[194:197], v[126:129]
	v_mfma_f32_16x16x32_bf16 v[126:129], v[162:165], v[198:201], v[126:129]
	v_mfma_f32_16x16x32_bf16 v[122:125], v[166:169], v[194:197], v[122:125]
	v_mfma_f32_16x16x32_bf16 v[122:125], v[170:173], v[198:201], v[122:125]
	v_mfma_f32_16x16x32_bf16 v[110:113], v[152:155], v[202:205], v[110:113]
	v_mfma_f32_16x16x32_bf16 v[110:113], v[162:165], v[206:209], v[110:113]
	v_mfma_f32_16x16x32_bf16 v[106:109], v[166:169], v[202:205], v[106:109]
	v_mfma_f32_16x16x32_bf16 v[106:109], v[170:173], v[206:209], v[106:109]
	v_mfma_f32_16x16x32_bf16 v[94:97], v[152:155], v[210:213], v[94:97]
	v_mfma_f32_16x16x32_bf16 v[94:97], v[162:165], v[214:217], v[94:97]
	v_mfma_f32_16x16x32_bf16 v[90:93], v[166:169], v[210:213], v[90:93]
	v_mfma_f32_16x16x32_bf16 v[90:93], v[170:173], v[214:217], v[90:93]
	v_mfma_f32_16x16x32_bf16 v[78:81], v[152:155], v[218:221], v[78:81]
	v_mfma_f32_16x16x32_bf16 v[78:81], v[162:165], v[222:225], v[78:81]
	v_mfma_f32_16x16x32_bf16 v[74:77], v[166:169], v[218:221], v[74:77]
	v_mfma_f32_16x16x32_bf16 v[74:77], v[170:173], v[222:225], v[74:77]
	v_mfma_f32_16x16x32_bf16 v[118:121], v[174:177], v[194:197], v[118:121]
	v_mfma_f32_16x16x32_bf16 v[118:121], v[182:185], v[198:201], v[118:121]
	v_mfma_f32_16x16x32_bf16 v[114:117], v[186:189], v[194:197], v[114:117]
	v_mfma_f32_16x16x32_bf16 v[114:117], v[190:193], v[198:201], v[114:117]
	v_mfma_f32_16x16x32_bf16 v[102:105], v[174:177], v[202:205], v[102:105]
	v_mfma_f32_16x16x32_bf16 v[102:105], v[182:185], v[206:209], v[102:105]
	v_mfma_f32_16x16x32_bf16 v[98:101], v[186:189], v[202:205], v[98:101]
	v_mfma_f32_16x16x32_bf16 v[98:101], v[190:193], v[206:209], v[98:101]
	v_mfma_f32_16x16x32_bf16 v[86:89], v[174:177], v[210:213], v[86:89]
	v_mfma_f32_16x16x32_bf16 v[86:89], v[182:185], v[214:217], v[86:89]
	v_mfma_f32_16x16x32_bf16 v[82:85], v[186:189], v[210:213], v[82:85]
	v_mfma_f32_16x16x32_bf16 v[82:85], v[190:193], v[214:217], v[82:85]
	v_mfma_f32_16x16x32_bf16 v[70:73], v[174:177], v[218:221], v[70:73]
	v_mfma_f32_16x16x32_bf16 v[70:73], v[182:185], v[222:225], v[70:73]
	v_mfma_f32_16x16x32_bf16 v[66:69], v[186:189], v[218:221], v[66:69]
	v_mfma_f32_16x16x32_bf16 v[66:69], v[190:193], v[222:225], v[66:69]
	s_barrier
	s_add_u32 s14, s14, 0x80
	s_addc_u32 s15, s15, 0
	s_add_i32 m0, s28, 0x18000
	ds_read_b128 v[194:197], v161 offset:49152
	ds_read_b128 v[198:201], v161 offset:50176
	global_load_lds_dwordx4 v144, s[14:15]
	s_add_i32 m0, s28, 0x1a000
	s_add_u32 s98, s98, 0x80
	s_addc_u32 s99, s99, 0
	ds_read_b128 v[202:205], v161 offset:51200
	global_load_lds_dwordx4 v140, s[14:15]
	s_add_i32 m0, s28, 0x1c000
	ds_read_b128 v[206:209], v161 offset:52224
	ds_read_b128 v[210:213], v161 offset:53248
	global_load_lds_dwordx4 v144, s[98:99]
	s_add_i32 m0, s28, 0x1e000
	s_add_u32 s16, s16, 0x80
	s_addc_u32 s17, s17, 0
	ds_read_b128 v[214:217], v161 offset:54272
	ds_read_b128 v[218:221], v161 offset:55296
	global_load_lds_dwordx4 v140, s[98:99]
	s_mov_b32 m0, s39
	ds_read_b128 v[222:225], v161 offset:56320
	global_load_lds_dwordx4 v146, s[16:17]
	s_mov_b32 m0, s44
	s_nop 0
	global_load_lds_dwordx4 v142, s[16:17]
	s_waitcnt vmcnt(8)
	s_waitcnt lgkmcnt(0)
	s_barrier
	v_mfma_f32_16x16x32_bf16 v[62:65], v[152:155], v[194:197], v[62:65]
	v_mfma_f32_16x16x32_bf16 v[62:65], v[162:165], v[198:201], v[62:65]
	v_mfma_f32_16x16x32_bf16 v[58:61], v[166:169], v[194:197], v[58:61]
	v_mfma_f32_16x16x32_bf16 v[58:61], v[170:173], v[198:201], v[58:61]
	v_mfma_f32_16x16x32_bf16 v[46:49], v[152:155], v[202:205], v[46:49]
	v_mfma_f32_16x16x32_bf16 v[46:49], v[162:165], v[206:209], v[46:49]
	v_mfma_f32_16x16x32_bf16 v[42:45], v[166:169], v[202:205], v[42:45]
	v_mfma_f32_16x16x32_bf16 v[42:45], v[170:173], v[206:209], v[42:45]
	v_mfma_f32_16x16x32_bf16 v[30:33], v[152:155], v[210:213], v[30:33]
	v_mfma_f32_16x16x32_bf16 v[30:33], v[162:165], v[214:217], v[30:33]
	v_mfma_f32_16x16x32_bf16 v[26:29], v[166:169], v[210:213], v[26:29]
	v_mfma_f32_16x16x32_bf16 v[26:29], v[170:173], v[214:217], v[26:29]
	v_mfma_f32_16x16x32_bf16 v[14:17], v[152:155], v[218:221], v[14:17]
	v_mfma_f32_16x16x32_bf16 v[14:17], v[162:165], v[222:225], v[14:17]
	v_mfma_f32_16x16x32_bf16 v[10:13], v[166:169], v[218:221], v[10:13]
	v_mfma_f32_16x16x32_bf16 v[10:13], v[170:173], v[222:225], v[10:13]
	v_mfma_f32_16x16x32_bf16 v[54:57], v[174:177], v[194:197], v[54:57]
	v_mfma_f32_16x16x32_bf16 v[54:57], v[182:185], v[198:201], v[54:57]
	v_mfma_f32_16x16x32_bf16 v[50:53], v[186:189], v[194:197], v[50:53]
	v_mfma_f32_16x16x32_bf16 v[50:53], v[190:193], v[198:201], v[50:53]
	v_mfma_f32_16x16x32_bf16 v[38:41], v[174:177], v[202:205], v[38:41]
	v_mfma_f32_16x16x32_bf16 v[38:41], v[182:185], v[206:209], v[38:41]
	v_mfma_f32_16x16x32_bf16 v[34:37], v[186:189], v[202:205], v[34:37]
	v_mfma_f32_16x16x32_bf16 v[34:37], v[190:193], v[206:209], v[34:37]
	v_mfma_f32_16x16x32_bf16 v[22:25], v[174:177], v[210:213], v[22:25]
	v_mfma_f32_16x16x32_bf16 v[22:25], v[182:185], v[214:217], v[22:25]
	v_mfma_f32_16x16x32_bf16 v[18:21], v[186:189], v[210:213], v[18:21]
	v_mfma_f32_16x16x32_bf16 v[18:21], v[190:193], v[214:217], v[18:21]
	v_mfma_f32_16x16x32_bf16 v[6:9], v[174:177], v[218:221], v[6:9]
	v_mfma_f32_16x16x32_bf16 v[6:9], v[182:185], v[222:225], v[6:9]
	v_mfma_f32_16x16x32_bf16 v[2:5], v[186:189], v[218:221], v[2:5]
	v_mfma_f32_16x16x32_bf16 v[2:5], v[190:193], v[222:225], v[2:5]
	s_barrier
	s_add_i32 s35, s35, 2
	s_add_u32 s12, s12, 0x100
	s_addc_u32 s13, s13, 0
	s_add_u32 s0, s0, 0x100
	s_addc_u32 s1, s1, 0
	s_cmp_gt_u32 s35, 61
	s_cbranch_scc0 .LBB0_572
	s_and_b64 vcc, exec, s[10:11]
	s_cbranch_vccz .LBB0_575
	s_barrier

.LBB0_882:
	s_add_u32 s20, s10, 0xfff00080
	s_addc_u32 s21, s11, -1
	s_add_i32 s22, 0, 0x10000
	s_cmp_eq_u32 s12, 60
	s_cselect_b32 s43, s55, s21
	s_cselect_b32 s42, s54, s20
	v_add_u32_e32 v2, s22, v155
	s_cselect_b32 s39, s37, s1
	s_cselect_b32 s38, s36, s0
	s_add_i32 s23, 0, 0x14000
	s_add_i32 m0, s29, 0xc000
	ds_read_b128 v[146:149], v2
	ds_read_b128 v[150:153], v2 offset:1024
	global_load_lds_dwordx4 v140, s[10:11]
	s_add_i32 m0, s29, 0xe000
	ds_read_b128 v[158:161], v2 offset:2048
	ds_read_b128 v[162:165], v2 offset:3072
	global_load_lds_dwordx4 v142, s[10:11]
	v_add_u32_e32 v2, s23, v155
	ds_read_b128 v[166:169], v2
	ds_read_b128 v[170:173], v2 offset:1024
	ds_read_b128 v[174:177], v2 offset:2048
	ds_read_b128 v[186:189], v2 offset:3072
	ds_read_b128 v[190:193], v157
	ds_read_b128 v[194:197], v157 offset:1024
	ds_read_b128 v[198:201], v157 offset:2048
	ds_read_b128 v[202:205], v157 offset:3072
	ds_read_b128 v[206:209], v157 offset:4096
	ds_read_b128 v[210:213], v157 offset:5120
	ds_read_b128 v[214:217], v157 offset:6144
	ds_read_b128 v[218:221], v157 offset:7168
	s_waitcnt vmcnt(8)
	s_waitcnt lgkmcnt(0)
	s_barrier
	v_mfma_f32_16x16x32_bf16 v[128:131], v[146:149], v[190:193], v[128:131]
	v_mfma_f32_16x16x32_bf16 v[128:131], v[150:153], v[194:197], v[128:131]
	v_mfma_f32_16x16x32_bf16 v[124:127], v[158:161], v[190:193], v[124:127]
	v_mfma_f32_16x16x32_bf16 v[124:127], v[162:165], v[194:197], v[124:127]
	v_mfma_f32_16x16x32_bf16 v[112:115], v[146:149], v[198:201], v[112:115]
	v_mfma_f32_16x16x32_bf16 v[112:115], v[150:153], v[202:205], v[112:115]
	v_mfma_f32_16x16x32_bf16 v[108:111], v[158:161], v[198:201], v[108:111]
	v_mfma_f32_16x16x32_bf16 v[108:111], v[162:165], v[202:205], v[108:111]
	v_mfma_f32_16x16x32_bf16 v[96:99], v[146:149], v[206:209], v[96:99]
	v_mfma_f32_16x16x32_bf16 v[96:99], v[150:153], v[210:213], v[96:99]
	v_mfma_f32_16x16x32_bf16 v[92:95], v[158:161], v[206:209], v[92:95]
	v_mfma_f32_16x16x32_bf16 v[92:95], v[162:165], v[210:213], v[92:95]
	v_mfma_f32_16x16x32_bf16 v[80:83], v[146:149], v[214:217], v[80:83]
	v_mfma_f32_16x16x32_bf16 v[80:83], v[150:153], v[218:221], v[80:83]
	v_mfma_f32_16x16x32_bf16 v[76:79], v[158:161], v[214:217], v[76:79]
	v_mfma_f32_16x16x32_bf16 v[76:79], v[162:165], v[218:221], v[76:79]
	v_mfma_f32_16x16x32_bf16 v[120:123], v[166:169], v[190:193], v[120:123]
	v_mfma_f32_16x16x32_bf16 v[120:123], v[170:173], v[194:197], v[120:123]
	v_mfma_f32_16x16x32_bf16 v[116:119], v[174:177], v[190:193], v[116:119]
	v_mfma_f32_16x16x32_bf16 v[116:119], v[186:189], v[194:197], v[116:119]
	v_mfma_f32_16x16x32_bf16 v[104:107], v[166:169], v[198:201], v[104:107]
	v_mfma_f32_16x16x32_bf16 v[104:107], v[170:173], v[202:205], v[104:107]
	v_mfma_f32_16x16x32_bf16 v[100:103], v[174:177], v[198:201], v[100:103]
	v_mfma_f32_16x16x32_bf16 v[100:103], v[186:189], v[202:205], v[100:103]
	v_mfma_f32_16x16x32_bf16 v[88:91], v[166:169], v[206:209], v[88:91]
	v_mfma_f32_16x16x32_bf16 v[88:91], v[170:173], v[210:213], v[88:91]
	v_mfma_f32_16x16x32_bf16 v[84:87], v[174:177], v[206:209], v[84:87]
	v_mfma_f32_16x16x32_bf16 v[84:87], v[186:189], v[210:213], v[84:87]
	v_mfma_f32_16x16x32_bf16 v[72:75], v[166:169], v[214:217], v[72:75]
	v_mfma_f32_16x16x32_bf16 v[72:75], v[170:173], v[218:221], v[72:75]
	v_mfma_f32_16x16x32_bf16 v[68:71], v[174:177], v[214:217], v[68:71]
	v_mfma_f32_16x16x32_bf16 v[68:71], v[186:189], v[218:221], v[68:71]
	s_barrier
	s_add_i32 m0, s58, 0x10000
	ds_read_b128 v[190:193], v157 offset:16384
	ds_read_b128 v[194:197], v157 offset:17408
	global_load_lds_dwordx4 v134, s[38:39]
	s_add_i32 m0, s58, 0x12000
	s_add_u32 s98, s38, 0x100000
	s_addc_u32 s99, s39, 0
	ds_read_b128 v[198:201], v157 offset:18432
	global_load_lds_dwordx4 v138, s[38:39]
	s_add_i32 m0, s58, 0x14000
	ds_read_b128 v[202:205], v157 offset:19456
	ds_read_b128 v[206:209], v157 offset:20480
	global_load_lds_dwordx4 v134, s[98:99]
	s_add_i32 m0, s58, 0x16000
	ds_read_b128 v[210:213], v157 offset:21504
	ds_read_b128 v[214:217], v157 offset:22528
	global_load_lds_dwordx4 v138, s[98:99]
	s_mov_b32 m0, s29
	ds_read_b128 v[218:221], v157 offset:23552
	global_load_lds_dwordx4 v132, s[42:43]
	s_mov_b32 m0, s31
	s_nop 0
	global_load_lds_dwordx4 v136, s[42:43]
	s_waitcnt vmcnt(8)
	s_waitcnt lgkmcnt(0)
	s_barrier
	v_mfma_f32_16x16x32_bf16 v[64:67], v[146:149], v[190:193], v[64:67]
	v_mfma_f32_16x16x32_bf16 v[64:67], v[150:153], v[194:197], v[64:67]
	v_mfma_f32_16x16x32_bf16 v[60:63], v[158:161], v[190:193], v[60:63]
	v_mfma_f32_16x16x32_bf16 v[60:63], v[162:165], v[194:197], v[60:63]
	v_mfma_f32_16x16x32_bf16 v[48:51], v[146:149], v[198:201], v[48:51]
	v_mfma_f32_16x16x32_bf16 v[48:51], v[150:153], v[202:205], v[48:51]
	v_mfma_f32_16x16x32_bf16 v[44:47], v[158:161], v[198:201], v[44:47]
	v_mfma_f32_16x16x32_bf16 v[44:47], v[162:165], v[202:205], v[44:47]
	v_mfma_f32_16x16x32_bf16 v[32:35], v[146:149], v[206:209], v[32:35]
	v_mfma_f32_16x16x32_bf16 v[32:35], v[150:153], v[210:213], v[32:35]
	v_mfma_f32_16x16x32_bf16 v[28:31], v[158:161], v[206:209], v[28:31]
	v_mfma_f32_16x16x32_bf16 v[28:31], v[162:165], v[210:213], v[28:31]
	v_mfma_f32_16x16x32_bf16 v[16:19], v[146:149], v[214:217], v[16:19]
	v_mfma_f32_16x16x32_bf16 v[16:19], v[150:153], v[218:221], v[16:19]
	v_mfma_f32_16x16x32_bf16 v[12:15], v[158:161], v[214:217], v[12:15]
	v_mfma_f32_16x16x32_bf16 v[12:15], v[162:165], v[218:221], v[12:15]
	v_mfma_f32_16x16x32_bf16 v[56:59], v[166:169], v[190:193], v[56:59]
	v_mfma_f32_16x16x32_bf16 v[56:59], v[170:173], v[194:197], v[56:59]
	v_mfma_f32_16x16x32_bf16 v[52:55], v[174:177], v[190:193], v[52:55]
	v_mfma_f32_16x16x32_bf16 v[52:55], v[186:189], v[194:197], v[52:55]
	v_mfma_f32_16x16x32_bf16 v[40:43], v[166:169], v[198:201], v[40:43]
	v_mfma_f32_16x16x32_bf16 v[40:43], v[170:173], v[202:205], v[40:43]
	v_mfma_f32_16x16x32_bf16 v[36:39], v[174:177], v[198:201], v[36:39]
	v_mfma_f32_16x16x32_bf16 v[36:39], v[186:189], v[202:205], v[36:39]
	v_mfma_f32_16x16x32_bf16 v[24:27], v[166:169], v[206:209], v[24:27]
	v_mfma_f32_16x16x32_bf16 v[24:27], v[170:173], v[210:213], v[24:27]
	v_mfma_f32_16x16x32_bf16 v[20:23], v[174:177], v[206:209], v[20:23]
	v_mfma_f32_16x16x32_bf16 v[20:23], v[186:189], v[210:213], v[20:23]
	v_mfma_f32_16x16x32_bf16 v[8:11], v[166:169], v[214:217], v[8:11]
	v_mfma_f32_16x16x32_bf16 v[8:11], v[170:173], v[218:221], v[8:11]
	v_mfma_f32_16x16x32_bf16 v[4:7], v[174:177], v[214:217], v[4:7]
	v_mfma_f32_16x16x32_bf16 v[4:7], v[186:189], v[218:221], v[4:7]
	s_barrier
	s_add_u32 s100, s42, 0x100000
	s_addc_u32 s101, s43, 0
	s_mov_b32 m0, s59
	s_add_i32 s22, 0, 0x18000
	v_add_u32_e32 v2, s22, v155
	s_add_i32 s23, 0, 0x1c000
	ds_read_b128 v[146:149], v2
	ds_read_b128 v[150:153], v2 offset:1024
	global_load_lds_dwordx4 v132, s[100:101]
	s_mov_b32 m0, s94
	ds_read_b128 v[158:161], v2 offset:2048
	ds_read_b128 v[162:165], v2 offset:3072
	global_load_lds_dwordx4 v136, s[100:101]
	v_add_u32_e32 v2, s23, v155
	ds_read_b128 v[166:169], v2
	ds_read_b128 v[170:173], v2 offset:1024
	ds_read_b128 v[174:177], v2 offset:2048
	ds_read_b128 v[186:189], v2 offset:3072
	ds_read_b128 v[190:193], v157 offset:32768
	ds_read_b128 v[194:197], v157 offset:33792
	ds_read_b128 v[198:201], v157 offset:34816
	ds_read_b128 v[202:205], v157 offset:35840
	ds_read_b128 v[206:209], v157 offset:36864
	ds_read_b128 v[210:213], v157 offset:37888
	ds_read_b128 v[214:217], v157 offset:38912
	ds_read_b128 v[218:221], v157 offset:39936
	s_waitcnt vmcnt(8)
	s_waitcnt lgkmcnt(0)
	s_barrier
	v_mfma_f32_16x16x32_bf16 v[128:131], v[146:149], v[190:193], v[128:131]
	v_mfma_f32_16x16x32_bf16 v[128:131], v[150:153], v[194:197], v[128:131]
	v_mfma_f32_16x16x32_bf16 v[124:127], v[158:161], v[190:193], v[124:127]
	v_mfma_f32_16x16x32_bf16 v[124:127], v[162:165], v[194:197], v[124:127]
	v_mfma_f32_16x16x32_bf16 v[112:115], v[146:149], v[198:201], v[112:115]
	v_mfma_f32_16x16x32_bf16 v[112:115], v[150:153], v[202:205], v[112:115]
	v_mfma_f32_16x16x32_bf16 v[108:111], v[158:161], v[198:201], v[108:111]
	v_mfma_f32_16x16x32_bf16 v[108:111], v[162:165], v[202:205], v[108:111]
	v_mfma_f32_16x16x32_bf16 v[96:99], v[146:149], v[206:209], v[96:99]
	v_mfma_f32_16x16x32_bf16 v[96:99], v[150:153], v[210:213], v[96:99]
	v_mfma_f32_16x16x32_bf16 v[92:95], v[158:161], v[206:209], v[92:95]
	v_mfma_f32_16x16x32_bf16 v[92:95], v[162:165], v[210:213], v[92:95]
	v_mfma_f32_16x16x32_bf16 v[80:83], v[146:149], v[214:217], v[80:83]
	v_mfma_f32_16x16x32_bf16 v[80:83], v[150:153], v[218:221], v[80:83]
	v_mfma_f32_16x16x32_bf16 v[76:79], v[158:161], v[214:217], v[76:79]
	v_mfma_f32_16x16x32_bf16 v[76:79], v[162:165], v[218:221], v[76:79]
	v_mfma_f32_16x16x32_bf16 v[120:123], v[166:169], v[190:193], v[120:123]
	v_mfma_f32_16x16x32_bf16 v[120:123], v[170:173], v[194:197], v[120:123]
	v_mfma_f32_16x16x32_bf16 v[116:119], v[174:177], v[190:193], v[116:119]
	v_mfma_f32_16x16x32_bf16 v[116:119], v[186:189], v[194:197], v[116:119]
	v_mfma_f32_16x16x32_bf16 v[104:107], v[166:169], v[198:201], v[104:107]
	v_mfma_f32_16x16x32_bf16 v[104:107], v[170:173], v[202:205], v[104:107]
	v_mfma_f32_16x16x32_bf16 v[100:103], v[174:177], v[198:201], v[100:103]
	v_mfma_f32_16x16x32_bf16 v[100:103], v[186:189], v[202:205], v[100:103]
	v_mfma_f32_16x16x32_bf16 v[88:91], v[166:169], v[206:209], v[88:91]
	v_mfma_f32_16x16x32_bf16 v[88:91], v[170:173], v[210:213], v[88:91]
	v_mfma_f32_16x16x32_bf16 v[84:87], v[174:177], v[206:209], v[84:87]
	v_mfma_f32_16x16x32_bf16 v[84:87], v[186:189], v[210:213], v[84:87]
	v_mfma_f32_16x16x32_bf16 v[72:75], v[166:169], v[214:217], v[72:75]
	v_mfma_f32_16x16x32_bf16 v[72:75], v[170:173], v[218:221], v[72:75]
	v_mfma_f32_16x16x32_bf16 v[68:71], v[174:177], v[214:217], v[68:71]
	v_mfma_f32_16x16x32_bf16 v[68:71], v[186:189], v[218:221], v[68:71]
	s_barrier
	s_add_u32 s38, s38, 0x80
	s_addc_u32 s39, s39, 0
	s_add_i32 m0, s58, 0x18000
	ds_read_b128 v[190:193], v157 offset:49152
	ds_read_b128 v[194:197], v157 offset:50176
	global_load_lds_dwordx4 v134, s[38:39]
	s_add_i32 m0, s58, 0x1a000
	s_add_u32 s98, s98, 0x80
	s_addc_u32 s99, s99, 0
	ds_read_b128 v[198:201], v157 offset:51200
	global_load_lds_dwordx4 v138, s[38:39]
	s_add_i32 m0, s58, 0x1c000
	ds_read_b128 v[202:205], v157 offset:52224
	ds_read_b128 v[206:209], v157 offset:53248
	global_load_lds_dwordx4 v134, s[98:99]
	s_add_i32 m0, s58, 0x1e000
	s_add_u32 s42, s42, 0x80
	s_addc_u32 s43, s43, 0
	ds_read_b128 v[210:213], v157 offset:54272
	ds_read_b128 v[214:217], v157 offset:55296
	global_load_lds_dwordx4 v138, s[98:99]
	s_mov_b32 m0, s14
	ds_read_b128 v[218:221], v157 offset:56320
	global_load_lds_dwordx4 v132, s[42:43]
	s_mov_b32 m0, s15
	s_nop 0
	global_load_lds_dwordx4 v136, s[42:43]
	s_waitcnt vmcnt(8)
	s_waitcnt lgkmcnt(0)
	s_barrier
	v_mfma_f32_16x16x32_bf16 v[64:67], v[146:149], v[190:193], v[64:67]
	v_mfma_f32_16x16x32_bf16 v[64:67], v[150:153], v[194:197], v[64:67]
	v_mfma_f32_16x16x32_bf16 v[60:63], v[158:161], v[190:193], v[60:63]
	v_mfma_f32_16x16x32_bf16 v[60:63], v[162:165], v[194:197], v[60:63]
	v_mfma_f32_16x16x32_bf16 v[48:51], v[146:149], v[198:201], v[48:51]
	v_mfma_f32_16x16x32_bf16 v[48:51], v[150:153], v[202:205], v[48:51]
	v_mfma_f32_16x16x32_bf16 v[44:47], v[158:161], v[198:201], v[44:47]
	v_mfma_f32_16x16x32_bf16 v[44:47], v[162:165], v[202:205], v[44:47]
	v_mfma_f32_16x16x32_bf16 v[32:35], v[146:149], v[206:209], v[32:35]
	v_mfma_f32_16x16x32_bf16 v[32:35], v[150:153], v[210:213], v[32:35]
	v_mfma_f32_16x16x32_bf16 v[28:31], v[158:161], v[206:209], v[28:31]
	v_mfma_f32_16x16x32_bf16 v[28:31], v[162:165], v[210:213], v[28:31]
	v_mfma_f32_16x16x32_bf16 v[16:19], v[146:149], v[214:217], v[16:19]
	v_mfma_f32_16x16x32_bf16 v[16:19], v[150:153], v[218:221], v[16:19]
	v_mfma_f32_16x16x32_bf16 v[12:15], v[158:161], v[214:217], v[12:15]
	v_mfma_f32_16x16x32_bf16 v[12:15], v[162:165], v[218:221], v[12:15]
	v_mfma_f32_16x16x32_bf16 v[56:59], v[166:169], v[190:193], v[56:59]
	v_mfma_f32_16x16x32_bf16 v[56:59], v[170:173], v[194:197], v[56:59]
	v_mfma_f32_16x16x32_bf16 v[52:55], v[174:177], v[190:193], v[52:55]
	v_mfma_f32_16x16x32_bf16 v[52:55], v[186:189], v[194:197], v[52:55]
	v_mfma_f32_16x16x32_bf16 v[40:43], v[166:169], v[198:201], v[40:43]
	v_mfma_f32_16x16x32_bf16 v[40:43], v[170:173], v[202:205], v[40:43]
	v_mfma_f32_16x16x32_bf16 v[36:39], v[174:177], v[198:201], v[36:39]
	v_mfma_f32_16x16x32_bf16 v[36:39], v[186:189], v[202:205], v[36:39]
	v_mfma_f32_16x16x32_bf16 v[24:27], v[166:169], v[206:209], v[24:27]
	v_mfma_f32_16x16x32_bf16 v[24:27], v[170:173], v[210:213], v[24:27]
	v_mfma_f32_16x16x32_bf16 v[20:23], v[174:177], v[206:209], v[20:23]
	v_mfma_f32_16x16x32_bf16 v[20:23], v[186:189], v[210:213], v[20:23]
	v_mfma_f32_16x16x32_bf16 v[8:11], v[166:169], v[214:217], v[8:11]
	v_mfma_f32_16x16x32_bf16 v[8:11], v[170:173], v[218:221], v[8:11]
	v_mfma_f32_16x16x32_bf16 v[4:7], v[174:177], v[214:217], v[4:7]
	v_mfma_f32_16x16x32_bf16 v[4:7], v[186:189], v[218:221], v[4:7]
	s_barrier
	s_add_i32 s12, s12, 2
	s_add_u32 s10, s10, 0x100
	s_addc_u32 s11, s11, 0
	s_add_u32 s0, s0, 0x100
	s_addc_u32 s1, s1, 0
	s_cmp_gt_u32 s12, 61
	s_cbranch_scc0 .LBB0_882
	s_and_b64 vcc, exec, s[48:49]
	s_cbranch_vccz .LBB0_885
	s_barrier

.LBB0_1226:
	s_add_u32 s21, s10, 0xfff00080
	s_addc_u32 s22, s11, -1
	s_add_i32 s23, 0, 0x10000
	s_cmp_eq_u32 s20, 60
	s_cselect_b32 s31, s53, s22
	s_cselect_b32 s30, s52, s21
	v_add_u32_e32 v2, s23, v151
	s_cselect_b32 s29, s55, s1
	s_cselect_b32 s28, s54, s0
	s_add_i32 s21, 0, 0x14000
	s_add_i32 m0, s8, 0xc000
	ds_read_b128 v[144:147], v2
	ds_read_b128 v[154:157], v2 offset:1024
	global_load_lds_dwordx4 v140, s[10:11]
	s_add_i32 m0, s8, 0xe000
	ds_read_b128 v[158:161], v2 offset:2048
	ds_read_b128 v[162:165], v2 offset:3072
	global_load_lds_dwordx4 v142, s[10:11]
	v_add_u32_e32 v2, s21, v151
	ds_read_b128 v[166:169], v2
	ds_read_b128 v[170:173], v2 offset:1024
	ds_read_b128 v[174:177], v2 offset:2048
	ds_read_b128 v[186:189], v2 offset:3072
	ds_read_b128 v[190:193], v153
	ds_read_b128 v[194:197], v153 offset:1024
	ds_read_b128 v[198:201], v153 offset:2048
	ds_read_b128 v[202:205], v153 offset:3072
	ds_read_b128 v[206:209], v153 offset:4096
	ds_read_b128 v[210:213], v153 offset:5120
	ds_read_b128 v[214:217], v153 offset:6144
	ds_read_b128 v[218:221], v153 offset:7168
	s_waitcnt vmcnt(8)
	s_waitcnt lgkmcnt(0)
	s_barrier
	v_mfma_f32_16x16x32_bf16 v[128:131], v[144:147], v[190:193], v[128:131]
	v_mfma_f32_16x16x32_bf16 v[128:131], v[154:157], v[194:197], v[128:131]
	v_mfma_f32_16x16x32_bf16 v[124:127], v[158:161], v[190:193], v[124:127]
	v_mfma_f32_16x16x32_bf16 v[124:127], v[162:165], v[194:197], v[124:127]
	v_mfma_f32_16x16x32_bf16 v[112:115], v[144:147], v[198:201], v[112:115]
	v_mfma_f32_16x16x32_bf16 v[112:115], v[154:157], v[202:205], v[112:115]
	v_mfma_f32_16x16x32_bf16 v[108:111], v[158:161], v[198:201], v[108:111]
	v_mfma_f32_16x16x32_bf16 v[108:111], v[162:165], v[202:205], v[108:111]
	v_mfma_f32_16x16x32_bf16 v[96:99], v[144:147], v[206:209], v[96:99]
	v_mfma_f32_16x16x32_bf16 v[96:99], v[154:157], v[210:213], v[96:99]
	v_mfma_f32_16x16x32_bf16 v[92:95], v[158:161], v[206:209], v[92:95]
	v_mfma_f32_16x16x32_bf16 v[92:95], v[162:165], v[210:213], v[92:95]
	v_mfma_f32_16x16x32_bf16 v[80:83], v[144:147], v[214:217], v[80:83]
	v_mfma_f32_16x16x32_bf16 v[80:83], v[154:157], v[218:221], v[80:83]
	v_mfma_f32_16x16x32_bf16 v[76:79], v[158:161], v[214:217], v[76:79]
	v_mfma_f32_16x16x32_bf16 v[76:79], v[162:165], v[218:221], v[76:79]
	v_mfma_f32_16x16x32_bf16 v[120:123], v[166:169], v[190:193], v[120:123]
	v_mfma_f32_16x16x32_bf16 v[120:123], v[170:173], v[194:197], v[120:123]
	v_mfma_f32_16x16x32_bf16 v[116:119], v[174:177], v[190:193], v[116:119]
	v_mfma_f32_16x16x32_bf16 v[116:119], v[186:189], v[194:197], v[116:119]
	v_mfma_f32_16x16x32_bf16 v[104:107], v[166:169], v[198:201], v[104:107]
	v_mfma_f32_16x16x32_bf16 v[104:107], v[170:173], v[202:205], v[104:107]
	v_mfma_f32_16x16x32_bf16 v[100:103], v[174:177], v[198:201], v[100:103]
	v_mfma_f32_16x16x32_bf16 v[100:103], v[186:189], v[202:205], v[100:103]
	v_mfma_f32_16x16x32_bf16 v[88:91], v[166:169], v[206:209], v[88:91]
	v_mfma_f32_16x16x32_bf16 v[88:91], v[170:173], v[210:213], v[88:91]
	v_mfma_f32_16x16x32_bf16 v[84:87], v[174:177], v[206:209], v[84:87]
	v_mfma_f32_16x16x32_bf16 v[84:87], v[186:189], v[210:213], v[84:87]
	v_mfma_f32_16x16x32_bf16 v[72:75], v[166:169], v[214:217], v[72:75]
	v_mfma_f32_16x16x32_bf16 v[72:75], v[170:173], v[218:221], v[72:75]
	v_mfma_f32_16x16x32_bf16 v[68:71], v[174:177], v[214:217], v[68:71]
	v_mfma_f32_16x16x32_bf16 v[68:71], v[186:189], v[218:221], v[68:71]
	s_barrier
	s_add_i32 m0, s38, 0x10000
	ds_read_b128 v[190:193], v153 offset:16384
	ds_read_b128 v[194:197], v153 offset:17408
	global_load_lds_dwordx4 v136, s[28:29]
	s_add_i32 m0, s38, 0x12000
	s_add_u32 s98, s28, 0x100000
	s_addc_u32 s99, s29, 0
	ds_read_b128 v[198:201], v153 offset:18432
	global_load_lds_dwordx4 v132, s[28:29]
	s_add_i32 m0, s38, 0x14000
	ds_read_b128 v[202:205], v153 offset:19456
	ds_read_b128 v[206:209], v153 offset:20480
	global_load_lds_dwordx4 v136, s[98:99]
	s_add_i32 m0, s38, 0x16000
	ds_read_b128 v[210:213], v153 offset:21504
	ds_read_b128 v[214:217], v153 offset:22528
	global_load_lds_dwordx4 v132, s[98:99]
	s_mov_b32 m0, s8
	ds_read_b128 v[218:221], v153 offset:23552
	global_load_lds_dwordx4 v138, s[30:31]
	s_mov_b32 m0, s9
	s_nop 0
	global_load_lds_dwordx4 v134, s[30:31]
	s_waitcnt vmcnt(8)
	s_waitcnt lgkmcnt(0)
	s_barrier
	v_mfma_f32_16x16x32_bf16 v[64:67], v[144:147], v[190:193], v[64:67]
	v_mfma_f32_16x16x32_bf16 v[64:67], v[154:157], v[194:197], v[64:67]
	v_mfma_f32_16x16x32_bf16 v[60:63], v[158:161], v[190:193], v[60:63]
	v_mfma_f32_16x16x32_bf16 v[60:63], v[162:165], v[194:197], v[60:63]
	v_mfma_f32_16x16x32_bf16 v[48:51], v[144:147], v[198:201], v[48:51]
	v_mfma_f32_16x16x32_bf16 v[48:51], v[154:157], v[202:205], v[48:51]
	v_mfma_f32_16x16x32_bf16 v[44:47], v[158:161], v[198:201], v[44:47]
	v_mfma_f32_16x16x32_bf16 v[44:47], v[162:165], v[202:205], v[44:47]
	v_mfma_f32_16x16x32_bf16 v[32:35], v[144:147], v[206:209], v[32:35]
	v_mfma_f32_16x16x32_bf16 v[32:35], v[154:157], v[210:213], v[32:35]
	v_mfma_f32_16x16x32_bf16 v[28:31], v[158:161], v[206:209], v[28:31]
	v_mfma_f32_16x16x32_bf16 v[28:31], v[162:165], v[210:213], v[28:31]
	v_mfma_f32_16x16x32_bf16 v[16:19], v[144:147], v[214:217], v[16:19]
	v_mfma_f32_16x16x32_bf16 v[16:19], v[154:157], v[218:221], v[16:19]
	v_mfma_f32_16x16x32_bf16 v[12:15], v[158:161], v[214:217], v[12:15]
	v_mfma_f32_16x16x32_bf16 v[12:15], v[162:165], v[218:221], v[12:15]
	v_mfma_f32_16x16x32_bf16 v[56:59], v[166:169], v[190:193], v[56:59]
	v_mfma_f32_16x16x32_bf16 v[56:59], v[170:173], v[194:197], v[56:59]
	v_mfma_f32_16x16x32_bf16 v[52:55], v[174:177], v[190:193], v[52:55]
	v_mfma_f32_16x16x32_bf16 v[52:55], v[186:189], v[194:197], v[52:55]
	v_mfma_f32_16x16x32_bf16 v[40:43], v[166:169], v[198:201], v[40:43]
	v_mfma_f32_16x16x32_bf16 v[40:43], v[170:173], v[202:205], v[40:43]
	v_mfma_f32_16x16x32_bf16 v[36:39], v[174:177], v[198:201], v[36:39]
	v_mfma_f32_16x16x32_bf16 v[36:39], v[186:189], v[202:205], v[36:39]
	v_mfma_f32_16x16x32_bf16 v[24:27], v[166:169], v[206:209], v[24:27]
	v_mfma_f32_16x16x32_bf16 v[24:27], v[170:173], v[210:213], v[24:27]
	v_mfma_f32_16x16x32_bf16 v[20:23], v[174:177], v[206:209], v[20:23]
	v_mfma_f32_16x16x32_bf16 v[20:23], v[186:189], v[210:213], v[20:23]
	v_mfma_f32_16x16x32_bf16 v[8:11], v[166:169], v[214:217], v[8:11]
	v_mfma_f32_16x16x32_bf16 v[8:11], v[170:173], v[218:221], v[8:11]
	v_mfma_f32_16x16x32_bf16 v[4:7], v[174:177], v[214:217], v[4:7]
	v_mfma_f32_16x16x32_bf16 v[4:7], v[186:189], v[218:221], v[4:7]
	s_barrier
	s_add_u32 s100, s30, 0x100000
	s_addc_u32 s101, s31, 0
	s_mov_b32 m0, s16
	s_add_i32 s21, 0, 0x18000
	v_add_u32_e32 v2, s21, v151
	s_add_i32 s24, 0, 0x1c000
	ds_read_b128 v[144:147], v2
	ds_read_b128 v[154:157], v2 offset:1024
	global_load_lds_dwordx4 v138, s[100:101]
	s_mov_b32 m0, s17
	ds_read_b128 v[158:161], v2 offset:2048
	ds_read_b128 v[162:165], v2 offset:3072
	global_load_lds_dwordx4 v134, s[100:101]
	v_add_u32_e32 v2, s24, v151
	ds_read_b128 v[166:169], v2
	ds_read_b128 v[170:173], v2 offset:1024
	ds_read_b128 v[174:177], v2 offset:2048
	ds_read_b128 v[186:189], v2 offset:3072
	ds_read_b128 v[190:193], v153 offset:32768
	ds_read_b128 v[194:197], v153 offset:33792
	ds_read_b128 v[198:201], v153 offset:34816
	ds_read_b128 v[202:205], v153 offset:35840
	ds_read_b128 v[206:209], v153 offset:36864
	ds_read_b128 v[210:213], v153 offset:37888
	ds_read_b128 v[214:217], v153 offset:38912
	ds_read_b128 v[218:221], v153 offset:39936
	s_waitcnt vmcnt(8)
	s_waitcnt lgkmcnt(0)
	s_barrier
	v_mfma_f32_16x16x32_bf16 v[128:131], v[144:147], v[190:193], v[128:131]
	v_mfma_f32_16x16x32_bf16 v[128:131], v[154:157], v[194:197], v[128:131]
	v_mfma_f32_16x16x32_bf16 v[124:127], v[158:161], v[190:193], v[124:127]
	v_mfma_f32_16x16x32_bf16 v[124:127], v[162:165], v[194:197], v[124:127]
	v_mfma_f32_16x16x32_bf16 v[112:115], v[144:147], v[198:201], v[112:115]
	v_mfma_f32_16x16x32_bf16 v[112:115], v[154:157], v[202:205], v[112:115]
	v_mfma_f32_16x16x32_bf16 v[108:111], v[158:161], v[198:201], v[108:111]
	v_mfma_f32_16x16x32_bf16 v[108:111], v[162:165], v[202:205], v[108:111]
	v_mfma_f32_16x16x32_bf16 v[96:99], v[144:147], v[206:209], v[96:99]
	v_mfma_f32_16x16x32_bf16 v[96:99], v[154:157], v[210:213], v[96:99]
	v_mfma_f32_16x16x32_bf16 v[92:95], v[158:161], v[206:209], v[92:95]
	v_mfma_f32_16x16x32_bf16 v[92:95], v[162:165], v[210:213], v[92:95]
	v_mfma_f32_16x16x32_bf16 v[80:83], v[144:147], v[214:217], v[80:83]
	v_mfma_f32_16x16x32_bf16 v[80:83], v[154:157], v[218:221], v[80:83]
	v_mfma_f32_16x16x32_bf16 v[76:79], v[158:161], v[214:217], v[76:79]
	v_mfma_f32_16x16x32_bf16 v[76:79], v[162:165], v[218:221], v[76:79]
	v_mfma_f32_16x16x32_bf16 v[120:123], v[166:169], v[190:193], v[120:123]
	v_mfma_f32_16x16x32_bf16 v[120:123], v[170:173], v[194:197], v[120:123]
	v_mfma_f32_16x16x32_bf16 v[116:119], v[174:177], v[190:193], v[116:119]
	v_mfma_f32_16x16x32_bf16 v[116:119], v[186:189], v[194:197], v[116:119]
	v_mfma_f32_16x16x32_bf16 v[104:107], v[166:169], v[198:201], v[104:107]
	v_mfma_f32_16x16x32_bf16 v[104:107], v[170:173], v[202:205], v[104:107]
	v_mfma_f32_16x16x32_bf16 v[100:103], v[174:177], v[198:201], v[100:103]
	v_mfma_f32_16x16x32_bf16 v[100:103], v[186:189], v[202:205], v[100:103]
	v_mfma_f32_16x16x32_bf16 v[88:91], v[166:169], v[206:209], v[88:91]
	v_mfma_f32_16x16x32_bf16 v[88:91], v[170:173], v[210:213], v[88:91]
	v_mfma_f32_16x16x32_bf16 v[84:87], v[174:177], v[206:209], v[84:87]
	v_mfma_f32_16x16x32_bf16 v[84:87], v[186:189], v[210:213], v[84:87]
	v_mfma_f32_16x16x32_bf16 v[72:75], v[166:169], v[214:217], v[72:75]
	v_mfma_f32_16x16x32_bf16 v[72:75], v[170:173], v[218:221], v[72:75]
	v_mfma_f32_16x16x32_bf16 v[68:71], v[174:177], v[214:217], v[68:71]
	v_mfma_f32_16x16x32_bf16 v[68:71], v[186:189], v[218:221], v[68:71]
	s_barrier
	s_add_u32 s28, s28, 0x80
	s_addc_u32 s29, s29, 0
	s_add_i32 m0, s38, 0x18000
	ds_read_b128 v[190:193], v153 offset:49152
	ds_read_b128 v[194:197], v153 offset:50176
	global_load_lds_dwordx4 v136, s[28:29]
	s_add_i32 m0, s38, 0x1a000
	s_add_u32 s98, s98, 0x80
	s_addc_u32 s99, s99, 0
	ds_read_b128 v[198:201], v153 offset:51200
	global_load_lds_dwordx4 v132, s[28:29]
	s_add_i32 m0, s38, 0x1c000
	ds_read_b128 v[202:205], v153 offset:52224
	ds_read_b128 v[206:209], v153 offset:53248
	global_load_lds_dwordx4 v136, s[98:99]
	s_add_i32 m0, s38, 0x1e000
	s_add_u32 s30, s30, 0x80
	s_addc_u32 s31, s31, 0
	ds_read_b128 v[210:213], v153 offset:54272
	ds_read_b128 v[214:217], v153 offset:55296
	global_load_lds_dwordx4 v132, s[98:99]
	s_mov_b32 m0, s45
	ds_read_b128 v[218:221], v153 offset:56320
	global_load_lds_dwordx4 v138, s[30:31]
	s_mov_b32 m0, s46
	s_nop 0
	global_load_lds_dwordx4 v134, s[30:31]
	s_waitcnt vmcnt(8)
	s_waitcnt lgkmcnt(0)
	s_barrier
	v_mfma_f32_16x16x32_bf16 v[64:67], v[144:147], v[190:193], v[64:67]
	v_mfma_f32_16x16x32_bf16 v[64:67], v[154:157], v[194:197], v[64:67]
	v_mfma_f32_16x16x32_bf16 v[60:63], v[158:161], v[190:193], v[60:63]
	v_mfma_f32_16x16x32_bf16 v[60:63], v[162:165], v[194:197], v[60:63]
	v_mfma_f32_16x16x32_bf16 v[48:51], v[144:147], v[198:201], v[48:51]
	v_mfma_f32_16x16x32_bf16 v[48:51], v[154:157], v[202:205], v[48:51]
	v_mfma_f32_16x16x32_bf16 v[44:47], v[158:161], v[198:201], v[44:47]
	v_mfma_f32_16x16x32_bf16 v[44:47], v[162:165], v[202:205], v[44:47]
	v_mfma_f32_16x16x32_bf16 v[32:35], v[144:147], v[206:209], v[32:35]
	v_mfma_f32_16x16x32_bf16 v[32:35], v[154:157], v[210:213], v[32:35]
	v_mfma_f32_16x16x32_bf16 v[28:31], v[158:161], v[206:209], v[28:31]
	v_mfma_f32_16x16x32_bf16 v[28:31], v[162:165], v[210:213], v[28:31]
	v_mfma_f32_16x16x32_bf16 v[16:19], v[144:147], v[214:217], v[16:19]
	v_mfma_f32_16x16x32_bf16 v[16:19], v[154:157], v[218:221], v[16:19]
	v_mfma_f32_16x16x32_bf16 v[12:15], v[158:161], v[214:217], v[12:15]
	v_mfma_f32_16x16x32_bf16 v[12:15], v[162:165], v[218:221], v[12:15]
	v_mfma_f32_16x16x32_bf16 v[56:59], v[166:169], v[190:193], v[56:59]
	v_mfma_f32_16x16x32_bf16 v[56:59], v[170:173], v[194:197], v[56:59]
	v_mfma_f32_16x16x32_bf16 v[52:55], v[174:177], v[190:193], v[52:55]
	v_mfma_f32_16x16x32_bf16 v[52:55], v[186:189], v[194:197], v[52:55]
	v_mfma_f32_16x16x32_bf16 v[40:43], v[166:169], v[198:201], v[40:43]
	v_mfma_f32_16x16x32_bf16 v[40:43], v[170:173], v[202:205], v[40:43]
	v_mfma_f32_16x16x32_bf16 v[36:39], v[174:177], v[198:201], v[36:39]
	v_mfma_f32_16x16x32_bf16 v[36:39], v[186:189], v[202:205], v[36:39]
	v_mfma_f32_16x16x32_bf16 v[24:27], v[166:169], v[206:209], v[24:27]
	v_mfma_f32_16x16x32_bf16 v[24:27], v[170:173], v[210:213], v[24:27]
	v_mfma_f32_16x16x32_bf16 v[20:23], v[174:177], v[206:209], v[20:23]
	v_mfma_f32_16x16x32_bf16 v[20:23], v[186:189], v[210:213], v[20:23]
	v_mfma_f32_16x16x32_bf16 v[8:11], v[166:169], v[214:217], v[8:11]
	v_mfma_f32_16x16x32_bf16 v[8:11], v[170:173], v[218:221], v[8:11]
	v_mfma_f32_16x16x32_bf16 v[4:7], v[174:177], v[214:217], v[4:7]
	v_mfma_f32_16x16x32_bf16 v[4:7], v[186:189], v[218:221], v[4:7]
	s_barrier
	s_add_i32 s20, s20, 2
	s_add_u32 s10, s10, 0x100
	s_addc_u32 s11, s11, 0
	s_add_u32 s0, s0, 0x100
	s_addc_u32 s1, s1, 0
	s_cmp_gt_u32 s20, 61
	s_cbranch_scc0 .LBB0_1226
	s_and_b64 vcc, exec, s[48:49]
	s_cbranch_vccz .LBB0_1229
	s_barrier
